# FFN-up s=0 with 16x16x32 bf16 MFMA shape (new LDS swizzle key and SWIGLU staging) instead of the 32x32x16 pipelined loop; without FFN-down K-loop changes
# baseline (speedup 1.0000x reference)
; DI float silu_f(float x) { return x * __builtin_amdgcn_rcpf(1.f + __expf(-x)); }
; template <int EPI, int MI>
; DI void gemm_tile(const GemmDesc& g, int tm, int tn, char* smem) {
;     ...
;   if (EPI == EPI_SWIGLU) {
;     u16* es = (u16*)smem;
; #pragma unroll
;     for (int mi = 0; mi < MI; ++mi)
; #pragma unroll
;       for (int i = 0; i < 16; ++i) {
;         const int lrow = wm * (32 * MI) + mi * 32 + (i & 3) + 8 * (i >> 2) + 4 * hh;
;         es[lrow * 64 + wn * 32 + r] = f2bf(silu_f(acc[mi][0][i]) * acc[mi][1][i]);
;       }
.LBB0_201:
	s_nop 3
	v_mul_f32_e32 v162, 0xbfb8aa3b, v0
	v_mul_f32_e32 v163, 0xbfb8aa3b, v1
	v_mul_f32_e32 v164, 0xbfb8aa3b, v2
	v_mul_f32_e32 v165, 0xbfb8aa3b, v3
	v_mul_f32_e32 v166, 0xbfb8aa3b, v4
	v_mul_f32_e32 v167, 0xbfb8aa3b, v5
	v_mul_f32_e32 v168, 0xbfb8aa3b, v6
	v_mul_f32_e32 v169, 0xbfb8aa3b, v7
	v_mul_f32_e32 v170, 0xbfb8aa3b, v16
	v_mul_f32_e32 v171, 0xbfb8aa3b, v17
	v_mul_f32_e32 v172, 0xbfb8aa3b, v18
	v_mul_f32_e32 v173, 0xbfb8aa3b, v19
	v_mul_f32_e32 v174, 0xbfb8aa3b, v20
	v_mul_f32_e32 v175, 0xbfb8aa3b, v21
	v_mul_f32_e32 v176, 0xbfb8aa3b, v22
	v_mul_f32_e32 v177, 0xbfb8aa3b, v23
	v_exp_f32_e32 v162, v162
	v_exp_f32_e32 v163, v163
	v_exp_f32_e32 v164, v164
	v_exp_f32_e32 v165, v165
	v_exp_f32_e32 v166, v166
	v_exp_f32_e32 v167, v167
	v_exp_f32_e32 v168, v168
	v_exp_f32_e32 v169, v169
	v_exp_f32_e32 v170, v170
	v_exp_f32_e32 v171, v171
	v_exp_f32_e32 v172, v172
	v_exp_f32_e32 v173, v173
	v_exp_f32_e32 v174, v174
	v_exp_f32_e32 v175, v175
	v_exp_f32_e32 v176, v176
	v_exp_f32_e32 v177, v177
	v_add_f32_e32 v162, 1.0, v162
	v_add_f32_e32 v163, 1.0, v163
	v_add_f32_e32 v164, 1.0, v164
	v_add_f32_e32 v165, 1.0, v165
	v_add_f32_e32 v166, 1.0, v166
	v_add_f32_e32 v167, 1.0, v167
	v_add_f32_e32 v168, 1.0, v168
	v_add_f32_e32 v169, 1.0, v169
	v_add_f32_e32 v170, 1.0, v170
	v_add_f32_e32 v171, 1.0, v171
	v_add_f32_e32 v172, 1.0, v172
	v_add_f32_e32 v173, 1.0, v173
	v_add_f32_e32 v174, 1.0, v174
	v_add_f32_e32 v175, 1.0, v175
	v_add_f32_e32 v176, 1.0, v176
	v_add_f32_e32 v177, 1.0, v177
	v_rcp_f32_e32 v162, v162
	v_rcp_f32_e32 v163, v163
	v_rcp_f32_e32 v164, v164
	v_rcp_f32_e32 v165, v165
	v_rcp_f32_e32 v166, v166
	v_rcp_f32_e32 v167, v167
	v_rcp_f32_e32 v168, v168
	v_rcp_f32_e32 v169, v169
	v_rcp_f32_e32 v170, v170
	v_rcp_f32_e32 v171, v171
	v_rcp_f32_e32 v172, v172
	v_rcp_f32_e32 v173, v173
	v_rcp_f32_e32 v174, v174
	v_rcp_f32_e32 v175, v175
	v_rcp_f32_e32 v176, v176
	v_rcp_f32_e32 v177, v177
	v_mul_f32_e32 v0, v0, v162
	v_mul_f32_e32 v1, v1, v163
	v_mul_f32_e32 v2, v2, v164
	v_mul_f32_e32 v3, v3, v165
	v_mul_f32_e32 v4, v4, v166
	v_mul_f32_e32 v5, v5, v167
	v_mul_f32_e32 v6, v6, v168
	v_mul_f32_e32 v7, v7, v169
	v_mul_f32_e32 v16, v16, v170
	v_mul_f32_e32 v17, v17, v171
	v_mul_f32_e32 v18, v18, v172
	v_mul_f32_e32 v19, v19, v173
	v_mul_f32_e32 v20, v20, v174
	v_mul_f32_e32 v21, v21, v175
	v_mul_f32_e32 v22, v22, v176
	v_mul_f32_e32 v23, v23, v177
	v_mul_f32_e32 v0, v8, v0
	v_mul_f32_e32 v1, v9, v1
	v_mul_f32_e32 v2, v10, v2
	v_mul_f32_e32 v3, v11, v3
	v_mul_f32_e32 v4, v12, v4
	v_mul_f32_e32 v5, v13, v5
	v_mul_f32_e32 v6, v14, v6
	v_mul_f32_e32 v7, v15, v7
	v_mul_f32_e32 v16, v24, v16
	v_mul_f32_e32 v17, v25, v17
	v_mul_f32_e32 v18, v26, v18
	v_mul_f32_e32 v19, v27, v19
	v_mul_f32_e32 v20, v28, v20
	v_mul_f32_e32 v21, v29, v21
	v_mul_f32_e32 v22, v30, v22
	v_mul_f32_e32 v23, v31, v23
	v_cvt_pk_bf16_f32 v0, v0, s0
	v_cvt_pk_bf16_f32 v1, v1, s0
	v_cvt_pk_bf16_f32 v2, v2, s0
	v_cvt_pk_bf16_f32 v3, v3, s0
	v_cvt_pk_bf16_f32 v4, v4, s0
	v_cvt_pk_bf16_f32 v5, v5, s0
	v_cvt_pk_bf16_f32 v6, v6, s0
	v_cvt_pk_bf16_f32 v7, v7, s0
	v_cvt_pk_bf16_f32 v16, v16, s0
	v_cvt_pk_bf16_f32 v17, v17, s0
	v_cvt_pk_bf16_f32 v18, v18, s0
	v_cvt_pk_bf16_f32 v19, v19, s0
	v_cvt_pk_bf16_f32 v20, v20, s0
	v_cvt_pk_bf16_f32 v21, v21, s0
	v_cvt_pk_bf16_f32 v22, v22, s0
	v_cvt_pk_bf16_f32 v23, v23, s0
	v_mul_f32_e32 v162, 0xbfb8aa3b, v32
	v_mul_f32_e32 v163, 0xbfb8aa3b, v33
	v_mul_f32_e32 v164, 0xbfb8aa3b, v34
	v_mul_f32_e32 v165, 0xbfb8aa3b, v35
	v_mul_f32_e32 v166, 0xbfb8aa3b, v36
	v_mul_f32_e32 v167, 0xbfb8aa3b, v37
	v_mul_f32_e32 v168, 0xbfb8aa3b, v38
	v_mul_f32_e32 v169, 0xbfb8aa3b, v39
	v_mul_f32_e32 v170, 0xbfb8aa3b, v48
	v_mul_f32_e32 v171, 0xbfb8aa3b, v49
	v_mul_f32_e32 v172, 0xbfb8aa3b, v50
	v_mul_f32_e32 v173, 0xbfb8aa3b, v51
	v_mul_f32_e32 v174, 0xbfb8aa3b, v52
	v_mul_f32_e32 v175, 0xbfb8aa3b, v53
	v_mul_f32_e32 v176, 0xbfb8aa3b, v54
	v_mul_f32_e32 v177, 0xbfb8aa3b, v55
	v_exp_f32_e32 v162, v162
	v_exp_f32_e32 v163, v163
	v_exp_f32_e32 v164, v164
	v_exp_f32_e32 v165, v165
	v_exp_f32_e32 v166, v166
	v_exp_f32_e32 v167, v167
	v_exp_f32_e32 v168, v168
	v_exp_f32_e32 v169, v169
	v_exp_f32_e32 v170, v170
	v_exp_f32_e32 v171, v171
	v_exp_f32_e32 v172, v172
	v_exp_f32_e32 v173, v173
	v_exp_f32_e32 v174, v174
	v_exp_f32_e32 v175, v175
	v_exp_f32_e32 v176, v176
	v_exp_f32_e32 v177, v177
	v_add_f32_e32 v162, 1.0, v162
	v_add_f32_e32 v163, 1.0, v163
	v_add_f32_e32 v164, 1.0, v164
	v_add_f32_e32 v165, 1.0, v165
	v_add_f32_e32 v166, 1.0, v166
	v_add_f32_e32 v167, 1.0, v167
	v_add_f32_e32 v168, 1.0, v168
	v_add_f32_e32 v169, 1.0, v169
	v_add_f32_e32 v170, 1.0, v170
	v_add_f32_e32 v171, 1.0, v171
	v_add_f32_e32 v172, 1.0, v172
	v_add_f32_e32 v173, 1.0, v173
	v_add_f32_e32 v174, 1.0, v174
	v_add_f32_e32 v175, 1.0, v175
	v_add_f32_e32 v176, 1.0, v176
	v_add_f32_e32 v177, 1.0, v177
	v_rcp_f32_e32 v162, v162
	v_rcp_f32_e32 v163, v163
	v_rcp_f32_e32 v164, v164
	v_rcp_f32_e32 v165, v165
	v_rcp_f32_e32 v166, v166
	v_rcp_f32_e32 v167, v167
	v_rcp_f32_e32 v168, v168
	v_rcp_f32_e32 v169, v169
	v_rcp_f32_e32 v170, v170
	v_rcp_f32_e32 v171, v171
	v_rcp_f32_e32 v172, v172
	v_rcp_f32_e32 v173, v173
	v_rcp_f32_e32 v174, v174
	v_rcp_f32_e32 v175, v175
	v_rcp_f32_e32 v176, v176
	v_rcp_f32_e32 v177, v177
	v_mul_f32_e32 v32, v32, v162
	v_mul_f32_e32 v33, v33, v163
	v_mul_f32_e32 v34, v34, v164
	v_mul_f32_e32 v35, v35, v165
	v_mul_f32_e32 v36, v36, v166
	v_mul_f32_e32 v37, v37, v167
	v_mul_f32_e32 v38, v38, v168
	v_mul_f32_e32 v39, v39, v169
	v_mul_f32_e32 v48, v48, v170
	v_mul_f32_e32 v49, v49, v171
	v_mul_f32_e32 v50, v50, v172
	v_mul_f32_e32 v51, v51, v173
	v_mul_f32_e32 v52, v52, v174
; DI float silu_f(float x) { return x * __builtin_amdgcn_rcpf(1.f + __expf(-x)); }
; template <int EPI, int MI>
; DI void gemm_tile(const GemmDesc& g, int tm, int tn, char* smem) {
;     ...
;   if (EPI == EPI_SWIGLU) {
;     u16* es = (u16*)smem;
; #pragma unroll
;     for (int mi = 0; mi < MI; ++mi)
; #pragma unroll
;       for (int i = 0; i < 16; ++i) {
;         const int lrow = wm * (32 * MI) + mi * 32 + (i & 3) + 8 * (i >> 2) + 4 * hh;
;         es[lrow * 64 + wn * 32 + r] = f2bf(silu_f(acc[mi][0][i]) * acc[mi][1][i]);
;       }
;     __syncthreads();
	v_mul_f32_e32 v53, v53, v175
	v_mul_f32_e32 v54, v54, v176
	v_mul_f32_e32 v55, v55, v177
	v_mul_f32_e32 v32, v40, v32
	v_mul_f32_e32 v33, v41, v33
	v_mul_f32_e32 v34, v42, v34
	v_mul_f32_e32 v35, v43, v35
	v_mul_f32_e32 v36, v44, v36
	v_mul_f32_e32 v37, v45, v37
	v_mul_f32_e32 v38, v46, v38
	v_mul_f32_e32 v39, v47, v39
	v_mul_f32_e32 v48, v56, v48
	v_mul_f32_e32 v49, v57, v49
	v_mul_f32_e32 v50, v58, v50
	v_mul_f32_e32 v51, v59, v51
	v_mul_f32_e32 v52, v60, v52
	v_mul_f32_e32 v53, v61, v53
	v_mul_f32_e32 v54, v62, v54
	v_mul_f32_e32 v55, v63, v55
	v_cvt_pk_bf16_f32 v32, v32, s0
	v_cvt_pk_bf16_f32 v33, v33, s0
	v_cvt_pk_bf16_f32 v34, v34, s0
	v_cvt_pk_bf16_f32 v35, v35, s0
	v_cvt_pk_bf16_f32 v36, v36, s0
	v_cvt_pk_bf16_f32 v37, v37, s0
	v_cvt_pk_bf16_f32 v38, v38, s0
	v_cvt_pk_bf16_f32 v39, v39, s0
	v_cvt_pk_bf16_f32 v48, v48, s0
	v_cvt_pk_bf16_f32 v49, v49, s0
	v_cvt_pk_bf16_f32 v50, v50, s0
	v_cvt_pk_bf16_f32 v51, v51, s0
	v_cvt_pk_bf16_f32 v52, v52, s0
	v_cvt_pk_bf16_f32 v53, v53, s0
	v_cvt_pk_bf16_f32 v54, v54, s0
	v_cvt_pk_bf16_f32 v55, v55, s0
	v_mul_f32_e32 v162, 0xbfb8aa3b, v64
	v_mul_f32_e32 v163, 0xbfb8aa3b, v65
	v_mul_f32_e32 v164, 0xbfb8aa3b, v66
	v_mul_f32_e32 v165, 0xbfb8aa3b, v67
	v_mul_f32_e32 v166, 0xbfb8aa3b, v68
	v_mul_f32_e32 v167, 0xbfb8aa3b, v69
	v_mul_f32_e32 v168, 0xbfb8aa3b, v70
	v_mul_f32_e32 v169, 0xbfb8aa3b, v71
	v_mul_f32_e32 v170, 0xbfb8aa3b, v80
	v_mul_f32_e32 v171, 0xbfb8aa3b, v81
	v_mul_f32_e32 v172, 0xbfb8aa3b, v82
	v_mul_f32_e32 v173, 0xbfb8aa3b, v83
	v_mul_f32_e32 v174, 0xbfb8aa3b, v84
	v_mul_f32_e32 v175, 0xbfb8aa3b, v85
	v_mul_f32_e32 v176, 0xbfb8aa3b, v86
	v_mul_f32_e32 v177, 0xbfb8aa3b, v87
	v_exp_f32_e32 v162, v162
	v_exp_f32_e32 v163, v163
	v_exp_f32_e32 v164, v164
	v_exp_f32_e32 v165, v165
	v_exp_f32_e32 v166, v166
	v_exp_f32_e32 v167, v167
	v_exp_f32_e32 v168, v168
	v_exp_f32_e32 v169, v169
	v_exp_f32_e32 v170, v170
	v_exp_f32_e32 v171, v171
	v_exp_f32_e32 v172, v172
	v_exp_f32_e32 v173, v173
	v_exp_f32_e32 v174, v174
	v_exp_f32_e32 v175, v175
	v_exp_f32_e32 v176, v176
	v_exp_f32_e32 v177, v177
	v_add_f32_e32 v162, 1.0, v162
	v_add_f32_e32 v163, 1.0, v163
	v_add_f32_e32 v164, 1.0, v164
	v_add_f32_e32 v165, 1.0, v165
	v_add_f32_e32 v166, 1.0, v166
	v_add_f32_e32 v167, 1.0, v167
	v_add_f32_e32 v168, 1.0, v168
	v_add_f32_e32 v169, 1.0, v169
	v_add_f32_e32 v170, 1.0, v170
	v_add_f32_e32 v171, 1.0, v171
	v_add_f32_e32 v172, 1.0, v172
	v_add_f32_e32 v173, 1.0, v173
	v_add_f32_e32 v174, 1.0, v174
	v_add_f32_e32 v175, 1.0, v175
	v_add_f32_e32 v176, 1.0, v176
	v_add_f32_e32 v177, 1.0, v177
	v_rcp_f32_e32 v162, v162
	v_rcp_f32_e32 v163, v163
	v_rcp_f32_e32 v164, v164
	v_rcp_f32_e32 v165, v165
	v_rcp_f32_e32 v166, v166
	v_rcp_f32_e32 v167, v167
	v_rcp_f32_e32 v168, v168
	v_rcp_f32_e32 v169, v169
	v_rcp_f32_e32 v170, v170
	v_rcp_f32_e32 v171, v171
	v_rcp_f32_e32 v172, v172
	v_rcp_f32_e32 v173, v173
	v_rcp_f32_e32 v174, v174
	v_rcp_f32_e32 v175, v175
	v_rcp_f32_e32 v176, v176
	v_rcp_f32_e32 v177, v177
	v_mul_f32_e32 v64, v64, v162
	v_mul_f32_e32 v65, v65, v163
	v_mul_f32_e32 v66, v66, v164
	v_mul_f32_e32 v67, v67, v165
	v_mul_f32_e32 v68, v68, v166
	v_mul_f32_e32 v69, v69, v167
	v_mul_f32_e32 v70, v70, v168
	v_mul_f32_e32 v71, v71, v169
	v_mul_f32_e32 v80, v80, v170
	v_mul_f32_e32 v81, v81, v171
	v_mul_f32_e32 v82, v82, v172
	v_mul_f32_e32 v83, v83, v173
	v_mul_f32_e32 v84, v84, v174
	v_mul_f32_e32 v85, v85, v175
	v_mul_f32_e32 v86, v86, v176
	v_mul_f32_e32 v87, v87, v177
	v_mul_f32_e32 v64, v72, v64
	v_mul_f32_e32 v65, v73, v65
	v_mul_f32_e32 v66, v74, v66
	v_mul_f32_e32 v67, v75, v67
	v_mul_f32_e32 v68, v76, v68
	v_mul_f32_e32 v69, v77, v69
	v_mul_f32_e32 v70, v78, v70
	v_mul_f32_e32 v71, v79, v71
	v_mul_f32_e32 v80, v88, v80
	v_mul_f32_e32 v81, v89, v81
	v_mul_f32_e32 v82, v90, v82
	v_mul_f32_e32 v83, v91, v83
	v_mul_f32_e32 v84, v92, v84
	v_mul_f32_e32 v85, v93, v85
	v_mul_f32_e32 v86, v94, v86
	v_mul_f32_e32 v87, v95, v87
	v_cvt_pk_bf16_f32 v64, v64, s0
	v_cvt_pk_bf16_f32 v65, v65, s0
	v_cvt_pk_bf16_f32 v66, v66, s0
	v_cvt_pk_bf16_f32 v67, v67, s0
	v_cvt_pk_bf16_f32 v68, v68, s0
	v_cvt_pk_bf16_f32 v69, v69, s0
	v_cvt_pk_bf16_f32 v70, v70, s0
	v_cvt_pk_bf16_f32 v71, v71, s0
	v_cvt_pk_bf16_f32 v80, v80, s0
	v_cvt_pk_bf16_f32 v81, v81, s0
	v_cvt_pk_bf16_f32 v82, v82, s0
	v_cvt_pk_bf16_f32 v83, v83, s0
	v_cvt_pk_bf16_f32 v84, v84, s0
	v_cvt_pk_bf16_f32 v85, v85, s0
	v_cvt_pk_bf16_f32 v86, v86, s0
	v_cvt_pk_bf16_f32 v87, v87, s0
	v_lshrrev_b32_e32 v162, 6, v132
	v_lshrrev_b32_e32 v163, 1, v162
	v_and_b32_e32 v162, 1, v162
	v_mul_u32_u24_e32 v163, 0x3000, v163
	v_lshl_add_u32 v163, v162, 6, v163
	v_bfe_u32 v162, v132, 4, 2
	v_lshl_add_u32 v163, v162, 9, v163
	v_and_b32_e32 v162, 15, v132
	v_lshl_add_u32 v163, v162, 1, v163
	ds_write_b16 v163, v0
	ds_write_b16 v163, v1 offset:128
	ds_write_b16 v163, v2 offset:256
	ds_write_b16 v163, v3 offset:384
	ds_write_b16 v163, v4 offset:32
	ds_write_b16 v163, v5 offset:160
	ds_write_b16 v163, v6 offset:288
	ds_write_b16 v163, v7 offset:416
	ds_write_b16 v163, v16 offset:2048
	ds_write_b16 v163, v17 offset:2176
	ds_write_b16 v163, v18 offset:2304
	ds_write_b16 v163, v19 offset:2432
	ds_write_b16 v163, v20 offset:2080
	ds_write_b16 v163, v21 offset:2208
	ds_write_b16 v163, v22 offset:2336
	ds_write_b16 v163, v23 offset:2464
	ds_write_b16 v163, v32 offset:4096
	ds_write_b16 v163, v33 offset:4224
	ds_write_b16 v163, v34 offset:4352
	ds_write_b16 v163, v35 offset:4480
	ds_write_b16 v163, v36 offset:4128
	ds_write_b16 v163, v37 offset:4256
	ds_write_b16 v163, v38 offset:4384
	ds_write_b16 v163, v39 offset:4512
	ds_write_b16 v163, v48 offset:6144
	ds_write_b16 v163, v49 offset:6272
	ds_write_b16 v163, v50 offset:6400
	ds_write_b16 v163, v51 offset:6528
	ds_write_b16 v163, v52 offset:6176
	ds_write_b16 v163, v53 offset:6304
	ds_write_b16 v163, v54 offset:6432
	ds_write_b16 v163, v55 offset:6560
	ds_write_b16 v163, v64 offset:8192
	ds_write_b16 v163, v65 offset:8320
	ds_write_b16 v163, v66 offset:8448
	ds_write_b16 v163, v67 offset:8576
	ds_write_b16 v163, v68 offset:8224
	ds_write_b16 v163, v69 offset:8352
	ds_write_b16 v163, v70 offset:8480
	ds_write_b16 v163, v71 offset:8608
	ds_write_b16 v163, v80 offset:10240
	ds_write_b16 v163, v81 offset:10368
	ds_write_b16 v163, v82 offset:10496
	ds_write_b16 v163, v83 offset:10624
	ds_write_b16 v163, v84 offset:10272
	ds_write_b16 v163, v85 offset:10400
	ds_write_b16 v163, v86 offset:10528
	ds_write_b16 v163, v87 offset:10656
	v_lshlrev_b32_e32 v99, 9, v122
	v_lshlrev_b32_e32 v100, 6, v123
	v_add3_u32 v99, 0, v99, v100
	v_lshlrev_b32_e32 v100, 1, v121
	v_readlane_b32 s16, v221, 5
	v_readlane_b32 s17, v221, 6
	s_movk_i32 s0, 0x3000
	v_mul_lo_u32 v64, v120, s0
	v_add3_u32 v64, v99, v100, v64
	s_movk_i32 s15, 0x1600
	v_lshlrev_b32_e32 v4, 4, v115
	v_mov_b32_e32 v5, v96
	v_mov_b64_e32 v[6:7], s[16:17]
	v_mad_i64_i32 v[8:9], s[16:17], v98, s15, v[6:7]
	v_add_u32_e32 v10, 0, v4
	v_lshl_add_u32 v0, v97, 7, v10
	s_waitcnt lgkmcnt(0)
	s_barrier
; template <int EPI, int MI>
; DI void gemm_tile(const GemmDesc& g, int tm, int tn, char* smem) {
;     ...
;   const int rowA = wm * (32 * MI) + r, rowB = wn * 64 + r;
;   const int hk = hh ^ ((r & 7) ^ ((r >> 3) & 3));
;     ...
;   G_GLDS(0, 0);
;   asm volatile("s_waitcnt vmcnt(0)" ::: "memory");
;   __syncthreads();
;     ...
; #pragma unroll
;     for (int j = 0; j < 2 * MI; ++j) {
;       const int lrow = (tid >> 3) + 32 * j, ch = tid & 7;
;       const u32x4 v = *(const u32x4*)(es + lrow * 64 + ch * 8);
;       *(u32x4*)(g.o16 + (size_t)(m0 + lrow) * g.ldo + (n0 >> 1) + ch * 8) = v;
;     }
;     __syncthreads();
	s_lshl_b32 s0, s39, 6
	ds_read_b128 v[0:3], v0
	s_ashr_i32 s1, s0, 31
	s_lshl_b64 s[0:1], s[0:1], 1
	v_lshl_add_u64 v[8:9], v[8:9], 0, s[0:1]
	v_lshl_add_u64 v[8:9], v[8:9], 0, v[4:5]
	s_waitcnt lgkmcnt(0)
	global_store_dwordx4 v[8:9], v[0:3], off
	v_add_u32_e32 v8, 32, v97
	s_nop 0
	v_lshl_add_u32 v0, v8, 7, v10
	ds_read_b128 v[0:3], v0
	v_add_u32_e32 v8, s38, v8
	v_mad_i64_i32 v[8:9], s[16:17], v8, s15, v[6:7]
	v_lshl_add_u64 v[8:9], v[8:9], 0, s[0:1]
	v_lshl_add_u64 v[8:9], v[8:9], 0, v[4:5]
	s_waitcnt lgkmcnt(0)
	global_store_dwordx4 v[8:9], v[0:3], off
	v_add_u32_e32 v8, 64, v97
	s_nop 0
	v_lshl_add_u32 v0, v8, 7, v10
	ds_read_b128 v[0:3], v0
	v_add_u32_e32 v8, s38, v8
	v_mad_i64_i32 v[8:9], s[16:17], v8, s15, v[6:7]
	v_lshl_add_u64 v[8:9], v[8:9], 0, s[0:1]
	v_lshl_add_u64 v[8:9], v[8:9], 0, v[4:5]
	s_waitcnt lgkmcnt(0)
	global_store_dwordx4 v[8:9], v[0:3], off
	v_add_u32_e32 v8, 0x60, v97
	s_nop 0
	v_lshl_add_u32 v0, v8, 7, v10
	ds_read_b128 v[0:3], v0
	v_add_u32_e32 v8, s38, v8
	v_mad_i64_i32 v[8:9], s[16:17], v8, s15, v[6:7]
	v_lshl_add_u64 v[8:9], v[8:9], 0, s[0:1]
	v_lshl_add_u64 v[8:9], v[8:9], 0, v[4:5]
	s_waitcnt lgkmcnt(0)
	global_store_dwordx4 v[8:9], v[0:3], off
	v_add_u32_e32 v8, 0x80, v97
	s_nop 0
	v_lshl_add_u32 v0, v8, 7, v10
	ds_read_b128 v[0:3], v0
	v_add_u32_e32 v8, s38, v8
	v_mad_i64_i32 v[8:9], s[16:17], v8, s15, v[6:7]
	v_lshl_add_u64 v[8:9], v[8:9], 0, s[0:1]
	v_lshl_add_u64 v[8:9], v[8:9], 0, v[4:5]
	s_waitcnt lgkmcnt(0)
	global_store_dwordx4 v[8:9], v[0:3], off
	v_add_u32_e32 v8, 0xa0, v97
	s_nop 0
	v_lshl_add_u32 v0, v8, 7, v10
	v_add_u32_e32 v8, s38, v8
	ds_read_b128 v[0:3], v0
	v_mad_i64_i32 v[6:7], s[16:17], v8, s15, v[6:7]
	v_lshl_add_u64 v[6:7], v[6:7], 0, s[0:1]
	v_readlane_b32 s0, v218, 38
	s_add_i32 s5, s5, s0
	v_readlane_b32 s0, v218, 31
	s_add_i32 s4, s4, s0
	v_readlane_b32 s0, v221, 7
	v_lshl_add_u64 v[4:5], v[6:7], 0, v[4:5]
	s_cmp_lt_i32 s5, s0
	s_waitcnt lgkmcnt(0)
	global_store_dwordx4 v[4:5], v[0:3], off
	s_barrier
	s_cbranch_scc0 .LBB0_198
.LBB0_202:
	s_abs_i32 s1, s5
	v_readlane_b32 s15, v219, 45
	s_mul_hi_u32 s15, s1, s15
	v_readlane_b32 s18, v219, 44
	s_mul_i32 s16, s15, s18
	s_sub_i32 s1, s1, s16
	s_ashr_i32 s0, s5, 31
	s_add_i32 s16, s15, 1
	s_sub_i32 s17, s1, s18
	s_cmp_ge_u32 s1, s18
	s_cselect_b32 s15, s16, s15
	s_cselect_b32 s1, s17, s1
	s_add_i32 s16, s15, 1
	s_cmp_ge_u32 s1, s18
	s_cselect_b32 s1, s16, s15
	s_xor_b32 s1, s1, s0
	s_sub_i32 s15, s1, s0
	s_mul_i32 s16, s15, s18
	s_sub_i32 s16, s5, s16
	s_abs_i32 s18, s16
	v_readlane_b32 s19, v219, 46
	s_mul_hi_u32 s19, s18, s19
	v_readlane_b32 s42, v218, 32
	s_mul_i32 s38, s19, s42
	s_sub_i32 s18, s18, s38
	s_ashr_i32 s17, s16, 31
	s_add_i32 s38, s19, 1
	s_sub_i32 s39, s18, s42
	s_cmp_ge_u32 s18, s42
	s_cselect_b32 s19, s38, s19
	s_cselect_b32 s18, s39, s18
	s_add_i32 s38, s19, 1
	s_cmp_ge_u32 s18, s42
	s_cselect_b32 s18, s38, s19
	s_xor_b32 s18, s18, s17
	s_sub_i32 s39, s18, s17
	s_sub_i32 s15, s15, s39
	v_mov_b32_e32 v4, v132
	s_mul_i32 s15, s15, s42
	s_add_i32 s16, s16, s54
	s_add_i32 s38, s16, s15
	v_ashrrev_i32_e32 v97, 3, v4
	v_ashrrev_i32_e32 v120, 7, v4
	v_bfe_u32 v0, v4, 6, 2
	v_xor_b32_e32 v1, v97, v4
	s_mulk_i32 s38, 0xc0
	v_and_b32_e32 v121, 31, v4
	v_bitop3_b32 v2, v1, v0, 7 bitop3:0x6c
	v_mul_lo_u32 v0, v120, s6
	v_and_b32_e32 v115, 7, v4
	v_or_b32_e32 v5, v0, v121
	v_lshrrev_b32_e32 v0, 3, v4
	s_waitcnt vmcnt(10)
	v_add_u32_e32 v98, s38, v97
	v_bfe_u32 v122, v4, 5, 1
	v_bitop3_b32 v0, v0, v115, 3 bitop3:0x6c
	v_ashrrev_i32_e32 v99, 31, v98
	v_xor_b32_e32 v6, v0, v122
	v_lshlrev_b64 v[0:1], 11, v[98:99]
	v_readlane_b32 s42, v223, 59
	v_lshlrev_b32_e32 v99, 4, v4
	v_readlane_b32 s43, v223, 60
	v_lshlrev_b32_e32 v100, 4, v2
	v_lshrrev_b32_e32 v100, 4, v132
	v_xor_b32_e32 v100, v100, v132
	v_and_b32_e32 v100, 7, v100
	v_lshlrev_b32_e32 v100, 4, v100
	v_lshl_add_u32 v2, s39, 7, v97
	v_add_u32_e32 v124, 0, v99
	v_lshl_add_u64 v[0:1], s[42:43], 0, v[0:1]
	v_mov_b32_e32 v101, v96
	v_ashrrev_i32_e32 v3, 31, v2
	v_readfirstlane_b32 s15, v124
	v_add_u32_e32 v125, 0x1000, v124
	v_lshl_add_u64 v[0:1], v[0:1], 0, v[100:101]
	v_lshlrev_b64 v[2:3], 11, v[2:3]
	s_mov_b32 m0, s15
	s_mov_b64 s[42:43], 0x10000
	v_readfirstlane_b32 s15, v125
	v_add_u32_e32 v126, 0x2000, v124
	s_waitcnt vmcnt(9)
	v_lshl_add_u64 v[102:103], s[70:71], 0, v[2:3]
	global_load_lds_dwordx4 v[0:1], off
	v_lshl_add_u64 v[2:3], v[0:1], 0, s[42:43]
	s_mov_b32 m0, s15
	s_mov_b64 s[44:45], 0x20000
	v_readfirstlane_b32 s15, v126
	v_add_u32_e32 v127, 0x3000, v124
	global_load_lds_dwordx4 v[2:3], off
	v_lshl_add_u64 v[2:3], v[0:1], 0, s[44:45]
	s_mov_b32 m0, s15
	s_mov_b64 s[46:47], 0x30000
	v_readfirstlane_b32 s15, v127
	v_add_u32_e32 v128, 0x4000, v124
	global_load_lds_dwordx4 v[2:3], off
	v_lshl_add_u64 v[2:3], v[0:1], 0, s[46:47]
	s_mov_b32 m0, s15
	s_mov_b64 s[52:53], 0x40000
	v_readfirstlane_b32 s15, v128
	v_add_u32_e32 v129, 0x5000, v124
	global_load_lds_dwordx4 v[2:3], off
	v_lshl_add_u64 v[2:3], v[0:1], 0, s[52:53]
	s_mov_b32 m0, s15
	s_mov_b64 s[52:53], 0x50000
	v_readfirstlane_b32 s15, v129
	v_add_u32_e32 v130, 0xc000, v124
	global_load_lds_dwordx4 v[2:3], off
	v_lshl_add_u64 v[0:1], v[0:1], 0, s[52:53]
	s_mov_b32 m0, s15
	v_readfirstlane_b32 s15, v130
	v_add_u32_e32 v131, 0xd000, v124
	global_load_lds_dwordx4 v[0:1], off
	v_lshl_add_u64 v[0:1], v[102:103], 0, v[100:101]
	s_mov_b32 m0, s15
	v_readfirstlane_b32 s15, v131
	v_add_u32_e32 v153, 0xe000, v124
	global_load_lds_dwordx4 v[0:1], off
	v_lshl_add_u64 v[2:3], v[0:1], 0, s[42:43]
	s_mov_b32 m0, s15
	v_readfirstlane_b32 s15, v153
	v_add_u32_e32 v154, 0xf000, v124
	global_load_lds_dwordx4 v[2:3], off
	v_lshl_add_u64 v[2:3], v[0:1], 0, s[44:45]
	s_mov_b32 m0, s15
	v_readfirstlane_b32 s15, v154
	global_load_lds_dwordx4 v[2:3], off
	v_lshl_add_u64 v[0:1], v[0:1], 0, s[46:47]
	s_mov_b32 m0, s15
	s_mul_i32 s0, s0, 43
	global_load_lds_dwordx4 v[0:1], off
	s_add_i32 s17, s17, s0
	s_sub_i32 s0, s17, s18
	s_mul_i32 s1, s1, 43
	s_sub_i32 s0, s0, s1
	v_readlane_b32 s1, v218, 33
	v_bfe_u32 v123, v4, 6, 1
	v_lshlrev_b32_e32 v0, 7, v121
	s_mul_i32 s0, s1, s0
	v_lshl_or_b32 v0, v123, 13, v0
	s_add_i32 s0, s0, s4
	v_add_u32_e32 v156, 0, v0
	v_add_u32_e32 v158, s10, v0
	v_add_u32_e32 v0, s0, v97
	v_ashrrev_i32_e32 v1, 31, v0
	s_waitcnt vmcnt(0)
; template <int EPI, int MI>
; DI void gemm_tile(const GemmDesc& g, int tm, int tn, char* smem) {
;     ...
;   f32x16 acc[MI][2];
; #pragma unroll
;   for (int a = 0; a < MI; ++a)
; #pragma unroll
;     for (int b = 0; b < 2; ++b)
; #pragma unroll
;       for (int i = 0; i < 16; ++i) acc[a][b][i] = 0.f;
;   const int srow = tid >> 3;
;   const int schunk = (tid & 7) ^ ((srow & 7) ^ ((srow >> 3) & 3));
;     ...
;   const int rowA = wm * (32 * MI) + r, rowB = wn * 64 + r;
;   const int hk = hh ^ ((r & 7) ^ ((r >> 3) & 3));
;     ...
;   G_GLDS(0, 0);
;   asm volatile("s_waitcnt vmcnt(0)" ::: "memory");
;   __syncthreads();
;   for (int kt = 0; kt < nk; kt += 2) {
;     if (kt + 1 < nk) G_GLDS(kt + 1, 1);
;     G_COMPUTE(0);
;     asm volatile("s_waitcnt vmcnt(0)" ::: "memory");
;     __syncthreads();
;     if (kt + 1 < nk) {
;       if (kt + 2 < nk) G_GLDS(kt + 2, 0);
;       G_COMPUTE(1);
;       asm volatile("s_waitcnt vmcnt(0)" ::: "memory");
;       __syncthreads();
;     }
;   }
	v_lshlrev_b64 v[0:1], 11, v[0:1]
	v_lshlrev_b32_e32 v157, 4, v6
	v_lshl_add_u64 v[104:105], s[70:71], 0, v[0:1]
	v_mov_b32_e32 v0, 0
	v_lshl_add_u32 v155, v5, 7, 0
	s_mov_b32 s15, 0
	v_mov_b32_e32 v1, v0
	v_mov_b32_e32 v2, v0
	v_mov_b32_e32 v3, v0
	v_mov_b32_e32 v4, v0
	v_mov_b32_e32 v5, v0
	v_mov_b32_e32 v6, v0
	v_mov_b32_e32 v7, v0
	v_mov_b32_e32 v8, v0
	v_mov_b32_e32 v9, v0
	v_mov_b32_e32 v10, v0
	v_mov_b32_e32 v11, v0
	v_mov_b32_e32 v12, v0
	v_mov_b32_e32 v13, v0
	v_mov_b32_e32 v14, v0
	v_mov_b32_e32 v15, v0
	v_mov_b32_e32 v16, v0
	v_mov_b32_e32 v17, v0
	v_mov_b32_e32 v18, v0
	v_mov_b32_e32 v19, v0
	v_mov_b32_e32 v20, v0
	v_mov_b32_e32 v21, v0
	v_mov_b32_e32 v22, v0
	v_mov_b32_e32 v23, v0
	v_mov_b32_e32 v24, v0
	v_mov_b32_e32 v25, v0
	v_mov_b32_e32 v26, v0
	v_mov_b32_e32 v27, v0
	v_mov_b32_e32 v28, v0
	v_mov_b32_e32 v29, v0
	v_mov_b32_e32 v30, v0
	v_mov_b32_e32 v31, v0
	v_mov_b32_e32 v32, v0
	v_mov_b32_e32 v33, v0
	v_mov_b32_e32 v34, v0
	v_mov_b32_e32 v35, v0
	v_mov_b32_e32 v36, v0
	v_mov_b32_e32 v37, v0
	v_mov_b32_e32 v38, v0
	v_mov_b32_e32 v39, v0
	v_mov_b32_e32 v40, v0
	v_mov_b32_e32 v41, v0
	v_mov_b32_e32 v42, v0
	v_mov_b32_e32 v43, v0
	v_mov_b32_e32 v44, v0
	v_mov_b32_e32 v45, v0
	v_mov_b32_e32 v46, v0
	v_mov_b32_e32 v47, v0
	v_mov_b32_e32 v48, v0
	s_waitcnt vmcnt(0)
	v_mov_b32_e32 v49, v0
	v_mov_b32_e32 v50, v0
	v_mov_b32_e32 v51, v0
	v_mov_b32_e32 v52, v0
	v_mov_b32_e32 v53, v0
	v_mov_b32_e32 v54, v0
	v_mov_b32_e32 v55, v0
	v_mov_b32_e32 v56, v0
	v_mov_b32_e32 v57, v0
	v_mov_b32_e32 v58, v0
	v_mov_b32_e32 v59, v0
	v_mov_b32_e32 v60, v0
	v_mov_b32_e32 v61, v0
	v_mov_b32_e32 v62, v0
	v_mov_b32_e32 v63, v0
	v_mov_b32_e32 v64, v0
	v_mov_b32_e32 v65, v0
	v_mov_b32_e32 v66, v0
	v_mov_b32_e32 v67, v0
	v_mov_b32_e32 v68, v0
	v_mov_b32_e32 v69, v0
	v_mov_b32_e32 v70, v0
	v_mov_b32_e32 v71, v0
	v_mov_b32_e32 v72, v0
	v_mov_b32_e32 v73, v0
	v_mov_b32_e32 v74, v0
	v_mov_b32_e32 v75, v0
	v_mov_b32_e32 v76, v0
	v_mov_b32_e32 v77, v0
	v_mov_b32_e32 v78, v0
	v_mov_b32_e32 v79, v0
	v_mov_b32_e32 v80, v0
	v_mov_b32_e32 v81, v0
	v_mov_b32_e32 v82, v0
	v_mov_b32_e32 v83, v0
	v_mov_b32_e32 v84, v0
	v_mov_b32_e32 v85, v0
	v_mov_b32_e32 v86, v0
	v_mov_b32_e32 v87, v0
	v_mov_b32_e32 v88, v0
	v_mov_b32_e32 v89, v0
	v_mov_b32_e32 v90, v0
	v_mov_b32_e32 v91, v0
	v_mov_b32_e32 v92, v0
	v_mov_b32_e32 v93, v0
	v_mov_b32_e32 v94, v0
	v_mov_b32_e32 v95, v0
	v_xor_b32_e32 v159, 32, v157
	v_xor_b32_e32 v160, 64, v157
	v_xor_b32_e32 v161, 0x60, v157
	s_mov_b64 s[18:19], 0x80
	s_mov_b64 s[42:43], 0x10080
	v_and_b32_e32 v108, 15, v132
	v_bfe_u32 v109, v132, 4, 2
	v_lshrrev_b32_e32 v253, 1, v108
	v_xor_b32_e32 v253, v253, v109
	v_lshlrev_b32_e32 v253, 4, v253
	v_lshl_add_u32 v253, v108, 7, v253
	v_lshrrev_b32_e32 v108, 6, v132
	v_lshrrev_b32_e32 v109, 1, v108
	v_and_b32_e32 v108, 1, v108
	v_mul_u32_u24_e32 v109, 0x3000, v109
	v_lshlrev_b32_e32 v108, 13, v108
	v_add_u32_e32 v252, v109, v253
	v_add_u32_e32 v254, v108, v253
	v_xor_b32_e32 v253, 64, v252
	v_xor_b32_e32 v255, 64, v254
	v_add_u32_e32 v106, 0x10000, v254
	v_add_u32_e32 v107, 0x10000, v255
	v_lshl_add_u64 v[104:105], v[104:105], 0, v[100:101]
	v_lshl_add_u64 v[102:103], v[102:103], 0, v[100:101]
	v_readfirstlane_b32 s100, v124
	s_waitcnt vmcnt(0) lgkmcnt(0)
	s_barrier
	ds_read_b128 v[236:239], v254 offset:49152
	ds_read_b128 v[240:243], v254 offset:51200
	ds_read_b128 v[244:247], v254 offset:53248
	ds_read_b128 v[248:251], v254 offset:55296
	ds_read_b128 v[224:227], v252
	ds_read_b128 v[228:231], v252 offset:2048
	s_mov_b32 s15, 0
.Lga16_loop:
	ds_read_b128 v[232:235], v252 offset:4096
	s_waitcnt lgkmcnt(2)
	v_mfma_f32_16x16x32_bf16 v[0:3], v[224:227], v[236:239], v[0:3]
	v_mfma_f32_16x16x32_bf16 v[4:7], v[224:227], v[240:243], v[4:7]
	v_mfma_f32_16x16x32_bf16 v[8:11], v[224:227], v[244:247], v[8:11]
	v_mfma_f32_16x16x32_bf16 v[12:15], v[224:227], v[248:251], v[12:15]
	s_add_u32 m0, s100, 0x6000
	v_lshl_add_u64 v[108:109], v[104:105], 0, s[96:97]
	global_load_lds_dwordx4 v[108:109], off
	ds_read_b128 v[224:227], v252 offset:6144
	s_waitcnt lgkmcnt(2)
	v_mfma_f32_16x16x32_bf16 v[16:19], v[228:231], v[236:239], v[16:19]
	v_mfma_f32_16x16x32_bf16 v[20:23], v[228:231], v[240:243], v[20:23]
	v_mfma_f32_16x16x32_bf16 v[24:27], v[228:231], v[244:247], v[24:27]
	v_mfma_f32_16x16x32_bf16 v[28:31], v[228:231], v[248:251], v[28:31]
	s_add_u32 m0, s100, 0x7000
	v_lshl_add_u64 v[108:109], v[104:105], 0, s[50:51]
	global_load_lds_dwordx4 v[108:109], off
	ds_read_b128 v[228:231], v252 offset:8192
	s_waitcnt lgkmcnt(2)
	v_mfma_f32_16x16x32_bf16 v[32:35], v[232:235], v[236:239], v[32:35]
	v_mfma_f32_16x16x32_bf16 v[36:39], v[232:235], v[240:243], v[36:39]
	v_mfma_f32_16x16x32_bf16 v[40:43], v[232:235], v[244:247], v[40:43]
	v_mfma_f32_16x16x32_bf16 v[44:47], v[232:235], v[248:251], v[44:47]
	s_add_u32 m0, s100, 0x8000
	v_lshl_add_u64 v[108:109], v[104:105], 0, s[24:25]
	global_load_lds_dwordx4 v[108:109], off
	ds_read_b128 v[232:235], v252 offset:10240
	s_waitcnt lgkmcnt(2)
	v_mfma_f32_16x16x32_bf16 v[48:51], v[224:227], v[236:239], v[48:51]
	v_mfma_f32_16x16x32_bf16 v[52:55], v[224:227], v[240:243], v[52:55]
	v_mfma_f32_16x16x32_bf16 v[56:59], v[224:227], v[244:247], v[56:59]
	v_mfma_f32_16x16x32_bf16 v[60:63], v[224:227], v[248:251], v[60:63]
	s_add_u32 m0, s100, 0x9000
	v_lshl_add_u64 v[108:109], v[104:105], 0, s[26:27]
	global_load_lds_dwordx4 v[108:109], off
	ds_read_b128 v[162:165], v255 offset:49152
	ds_read_b128 v[166:169], v255 offset:51200
	ds_read_b128 v[170:173], v255 offset:53248
	ds_read_b128 v[174:177], v255 offset:55296
	ds_read_b128 v[224:227], v253
	s_waitcnt lgkmcnt(6)
; template <int EPI, int MI>
; DI void gemm_tile(const GemmDesc& g, int tm, int tn, char* smem) {
;     ...
;   G_GLDS(0, 0);
;   asm volatile("s_waitcnt vmcnt(0)" ::: "memory");
;   __syncthreads();
;   for (int kt = 0; kt < nk; kt += 2) {
;     if (kt + 1 < nk) G_GLDS(kt + 1, 1);
;     G_COMPUTE(0);
;     asm volatile("s_waitcnt vmcnt(0)" ::: "memory");
;     __syncthreads();
;     if (kt + 1 < nk) {
;       if (kt + 2 < nk) G_GLDS(kt + 2, 0);
;       G_COMPUTE(1);
;       asm volatile("s_waitcnt vmcnt(0)" ::: "memory");
;       __syncthreads();
;     }
;   }
	v_mfma_f32_16x16x32_bf16 v[64:67], v[228:231], v[236:239], v[64:67]
	v_mfma_f32_16x16x32_bf16 v[68:71], v[228:231], v[240:243], v[68:71]
	v_mfma_f32_16x16x32_bf16 v[72:75], v[228:231], v[244:247], v[72:75]
	v_mfma_f32_16x16x32_bf16 v[76:79], v[228:231], v[248:251], v[76:79]
	s_add_u32 m0, s100, 0xa000
	v_lshl_add_u64 v[108:109], v[104:105], 0, s[28:29]
	global_load_lds_dwordx4 v[108:109], off
	ds_read_b128 v[228:231], v253 offset:2048
	s_waitcnt lgkmcnt(6)
	v_mfma_f32_16x16x32_bf16 v[80:83], v[232:235], v[236:239], v[80:83]
	v_mfma_f32_16x16x32_bf16 v[84:87], v[232:235], v[240:243], v[84:87]
	v_mfma_f32_16x16x32_bf16 v[88:91], v[232:235], v[244:247], v[88:91]
	v_mfma_f32_16x16x32_bf16 v[92:95], v[232:235], v[248:251], v[92:95]
	s_add_u32 m0, s100, 0xb000
	v_lshl_add_u64 v[108:109], v[104:105], 0, s[30:31]
	global_load_lds_dwordx4 v[108:109], off
	v_lshl_add_u64 v[104:105], v[104:105], 0, s[18:19]
	ds_read_b128 v[232:235], v253 offset:4096
	s_waitcnt lgkmcnt(2)
	v_mfma_f32_16x16x32_bf16 v[0:3], v[224:227], v[162:165], v[0:3]
	v_mfma_f32_16x16x32_bf16 v[4:7], v[224:227], v[166:169], v[4:7]
	v_mfma_f32_16x16x32_bf16 v[8:11], v[224:227], v[170:173], v[8:11]
	v_mfma_f32_16x16x32_bf16 v[12:15], v[224:227], v[174:177], v[12:15]
	s_add_u32 m0, s100, 0x10000
	v_lshl_add_u64 v[108:109], v[102:103], 0, s[18:19]
	global_load_lds_dwordx4 v[108:109], off
	ds_read_b128 v[224:227], v253 offset:6144
	s_waitcnt lgkmcnt(2)
	v_mfma_f32_16x16x32_bf16 v[16:19], v[228:231], v[162:165], v[16:19]
	v_mfma_f32_16x16x32_bf16 v[20:23], v[228:231], v[166:169], v[20:23]
	v_mfma_f32_16x16x32_bf16 v[24:27], v[228:231], v[170:173], v[24:27]
	v_mfma_f32_16x16x32_bf16 v[28:31], v[228:231], v[174:177], v[28:31]
	s_add_u32 m0, s100, 0x11000
	v_lshl_add_u64 v[108:109], v[102:103], 0, s[42:43]
	global_load_lds_dwordx4 v[108:109], off
	ds_read_b128 v[228:231], v253 offset:8192
	s_waitcnt lgkmcnt(2)
	v_mfma_f32_16x16x32_bf16 v[32:35], v[232:235], v[162:165], v[32:35]
	v_mfma_f32_16x16x32_bf16 v[36:39], v[232:235], v[166:169], v[36:39]
	v_mfma_f32_16x16x32_bf16 v[40:43], v[232:235], v[170:173], v[40:43]
	v_mfma_f32_16x16x32_bf16 v[44:47], v[232:235], v[174:177], v[44:47]
	s_mov_b64 s[16:17], 0x20080
	s_add_u32 m0, s100, 0x12000
	v_lshl_add_u64 v[108:109], v[102:103], 0, s[16:17]
	global_load_lds_dwordx4 v[108:109], off
	ds_read_b128 v[232:235], v253 offset:10240
	s_waitcnt lgkmcnt(2)
	v_mfma_f32_16x16x32_bf16 v[48:51], v[224:227], v[162:165], v[48:51]
	v_mfma_f32_16x16x32_bf16 v[52:55], v[224:227], v[166:169], v[52:55]
	v_mfma_f32_16x16x32_bf16 v[56:59], v[224:227], v[170:173], v[56:59]
	v_mfma_f32_16x16x32_bf16 v[60:63], v[224:227], v[174:177], v[60:63]
	s_mov_b64 s[16:17], 0x30080
	s_add_u32 m0, s100, 0x13000
	v_lshl_add_u64 v[108:109], v[102:103], 0, s[16:17]
	global_load_lds_dwordx4 v[108:109], off
	v_lshl_add_u64 v[102:103], v[102:103], 0, s[18:19]
	s_waitcnt lgkmcnt(0)
	s_waitcnt vmcnt(0)
	s_barrier
	ds_read_b128 v[236:239], v106
	ds_read_b128 v[240:243], v106 offset:2048
	ds_read_b128 v[244:247], v106 offset:4096
	ds_read_b128 v[248:251], v106 offset:6144
	ds_read_b128 v[224:227], v252 offset:24576
	v_mfma_f32_16x16x32_bf16 v[64:67], v[228:231], v[162:165], v[64:67]
	v_mfma_f32_16x16x32_bf16 v[68:71], v[228:231], v[166:169], v[68:71]
	v_mfma_f32_16x16x32_bf16 v[72:75], v[228:231], v[170:173], v[72:75]
	v_mfma_f32_16x16x32_bf16 v[76:79], v[228:231], v[174:177], v[76:79]
	ds_read_b128 v[228:231], v252 offset:26624
	v_mfma_f32_16x16x32_bf16 v[80:83], v[232:235], v[162:165], v[80:83]
	v_mfma_f32_16x16x32_bf16 v[84:87], v[232:235], v[166:169], v[84:87]
	v_mfma_f32_16x16x32_bf16 v[88:91], v[232:235], v[170:173], v[88:91]
	v_mfma_f32_16x16x32_bf16 v[92:95], v[232:235], v[174:177], v[92:95]
	s_cmp_eq_u32 s15, 14
	s_cbranch_scc1 .Lga16_last
	ds_read_b128 v[232:235], v252 offset:28672
	s_waitcnt lgkmcnt(2)
	v_mfma_f32_16x16x32_bf16 v[0:3], v[224:227], v[236:239], v[0:3]
	v_mfma_f32_16x16x32_bf16 v[4:7], v[224:227], v[240:243], v[4:7]
	v_mfma_f32_16x16x32_bf16 v[8:11], v[224:227], v[244:247], v[8:11]
	v_mfma_f32_16x16x32_bf16 v[12:15], v[224:227], v[248:251], v[12:15]
	s_mov_b32 m0, s100
	v_lshl_add_u64 v[108:109], v[104:105], 0, s[96:97]
	global_load_lds_dwordx4 v[108:109], off
	ds_read_b128 v[224:227], v252 offset:30720
	s_waitcnt lgkmcnt(2)
	v_mfma_f32_16x16x32_bf16 v[16:19], v[228:231], v[236:239], v[16:19]
	v_mfma_f32_16x16x32_bf16 v[20:23], v[228:231], v[240:243], v[20:23]
	v_mfma_f32_16x16x32_bf16 v[24:27], v[228:231], v[244:247], v[24:27]
	v_mfma_f32_16x16x32_bf16 v[28:31], v[228:231], v[248:251], v[28:31]
	s_add_u32 m0, s100, 0x1000
	v_lshl_add_u64 v[108:109], v[104:105], 0, s[50:51]
	global_load_lds_dwordx4 v[108:109], off
	ds_read_b128 v[228:231], v252 offset:32768
	s_waitcnt lgkmcnt(2)
	v_mfma_f32_16x16x32_bf16 v[32:35], v[232:235], v[236:239], v[32:35]
	v_mfma_f32_16x16x32_bf16 v[36:39], v[232:235], v[240:243], v[36:39]
	v_mfma_f32_16x16x32_bf16 v[40:43], v[232:235], v[244:247], v[40:43]
	v_mfma_f32_16x16x32_bf16 v[44:47], v[232:235], v[248:251], v[44:47]
	s_add_u32 m0, s100, 0x2000
	v_lshl_add_u64 v[108:109], v[104:105], 0, s[24:25]
	global_load_lds_dwordx4 v[108:109], off
	ds_read_b128 v[232:235], v252 offset:34816
	s_waitcnt lgkmcnt(2)
	v_mfma_f32_16x16x32_bf16 v[48:51], v[224:227], v[236:239], v[48:51]
	v_mfma_f32_16x16x32_bf16 v[52:55], v[224:227], v[240:243], v[52:55]
	v_mfma_f32_16x16x32_bf16 v[56:59], v[224:227], v[244:247], v[56:59]
	v_mfma_f32_16x16x32_bf16 v[60:63], v[224:227], v[248:251], v[60:63]
	s_add_u32 m0, s100, 0x3000
	v_lshl_add_u64 v[108:109], v[104:105], 0, s[26:27]
	global_load_lds_dwordx4 v[108:109], off
	ds_read_b128 v[162:165], v107
	ds_read_b128 v[166:169], v107 offset:2048
	ds_read_b128 v[170:173], v107 offset:4096
	ds_read_b128 v[174:177], v107 offset:6144
	ds_read_b128 v[224:227], v253 offset:24576
	s_waitcnt lgkmcnt(6)
; template <int EPI, int MI>
; DI void gemm_tile(const GemmDesc& g, int tm, int tn, char* smem) {
;     ...
;   G_GLDS(0, 0);
;   asm volatile("s_waitcnt vmcnt(0)" ::: "memory");
;   __syncthreads();
;   for (int kt = 0; kt < nk; kt += 2) {
;     if (kt + 1 < nk) G_GLDS(kt + 1, 1);
;     G_COMPUTE(0);
;     asm volatile("s_waitcnt vmcnt(0)" ::: "memory");
;     __syncthreads();
;     if (kt + 1 < nk) {
;       if (kt + 2 < nk) G_GLDS(kt + 2, 0);
;       G_COMPUTE(1);
;       asm volatile("s_waitcnt vmcnt(0)" ::: "memory");
;       __syncthreads();
;     }
;   }
	v_mfma_f32_16x16x32_bf16 v[64:67], v[228:231], v[236:239], v[64:67]
	v_mfma_f32_16x16x32_bf16 v[68:71], v[228:231], v[240:243], v[68:71]
	v_mfma_f32_16x16x32_bf16 v[72:75], v[228:231], v[244:247], v[72:75]
	v_mfma_f32_16x16x32_bf16 v[76:79], v[228:231], v[248:251], v[76:79]
	s_add_u32 m0, s100, 0x4000
	v_lshl_add_u64 v[108:109], v[104:105], 0, s[28:29]
	global_load_lds_dwordx4 v[108:109], off
	ds_read_b128 v[228:231], v253 offset:26624
	s_waitcnt lgkmcnt(6)
	v_mfma_f32_16x16x32_bf16 v[80:83], v[232:235], v[236:239], v[80:83]
	v_mfma_f32_16x16x32_bf16 v[84:87], v[232:235], v[240:243], v[84:87]
	v_mfma_f32_16x16x32_bf16 v[88:91], v[232:235], v[244:247], v[88:91]
	v_mfma_f32_16x16x32_bf16 v[92:95], v[232:235], v[248:251], v[92:95]
	s_add_u32 m0, s100, 0x5000
	v_lshl_add_u64 v[108:109], v[104:105], 0, s[30:31]
	global_load_lds_dwordx4 v[108:109], off
	v_lshl_add_u64 v[104:105], v[104:105], 0, s[18:19]
	ds_read_b128 v[232:235], v253 offset:28672
	s_waitcnt lgkmcnt(2)
	v_mfma_f32_16x16x32_bf16 v[0:3], v[224:227], v[162:165], v[0:3]
	v_mfma_f32_16x16x32_bf16 v[4:7], v[224:227], v[166:169], v[4:7]
	v_mfma_f32_16x16x32_bf16 v[8:11], v[224:227], v[170:173], v[8:11]
	v_mfma_f32_16x16x32_bf16 v[12:15], v[224:227], v[174:177], v[12:15]
	s_add_u32 m0, s100, 0xc000
	v_lshl_add_u64 v[108:109], v[102:103], 0, s[18:19]
	global_load_lds_dwordx4 v[108:109], off
	ds_read_b128 v[224:227], v253 offset:30720
	s_waitcnt lgkmcnt(2)
	v_mfma_f32_16x16x32_bf16 v[16:19], v[228:231], v[162:165], v[16:19]
	v_mfma_f32_16x16x32_bf16 v[20:23], v[228:231], v[166:169], v[20:23]
	v_mfma_f32_16x16x32_bf16 v[24:27], v[228:231], v[170:173], v[24:27]
	v_mfma_f32_16x16x32_bf16 v[28:31], v[228:231], v[174:177], v[28:31]
	s_add_u32 m0, s100, 0xd000
	v_lshl_add_u64 v[108:109], v[102:103], 0, s[42:43]
	global_load_lds_dwordx4 v[108:109], off
	ds_read_b128 v[228:231], v253 offset:32768
	s_waitcnt lgkmcnt(2)
	v_mfma_f32_16x16x32_bf16 v[32:35], v[232:235], v[162:165], v[32:35]
	v_mfma_f32_16x16x32_bf16 v[36:39], v[232:235], v[166:169], v[36:39]
	v_mfma_f32_16x16x32_bf16 v[40:43], v[232:235], v[170:173], v[40:43]
	v_mfma_f32_16x16x32_bf16 v[44:47], v[232:235], v[174:177], v[44:47]
	s_mov_b64 s[16:17], 0x20080
	s_add_u32 m0, s100, 0xe000
	v_lshl_add_u64 v[108:109], v[102:103], 0, s[16:17]
	global_load_lds_dwordx4 v[108:109], off
	ds_read_b128 v[232:235], v253 offset:34816
	s_waitcnt lgkmcnt(2)
	v_mfma_f32_16x16x32_bf16 v[48:51], v[224:227], v[162:165], v[48:51]
	v_mfma_f32_16x16x32_bf16 v[52:55], v[224:227], v[166:169], v[52:55]
	v_mfma_f32_16x16x32_bf16 v[56:59], v[224:227], v[170:173], v[56:59]
	v_mfma_f32_16x16x32_bf16 v[60:63], v[224:227], v[174:177], v[60:63]
	s_mov_b64 s[16:17], 0x30080
	s_add_u32 m0, s100, 0xf000
	v_lshl_add_u64 v[108:109], v[102:103], 0, s[16:17]
	global_load_lds_dwordx4 v[108:109], off
	v_lshl_add_u64 v[102:103], v[102:103], 0, s[18:19]
	s_waitcnt lgkmcnt(0)
	s_waitcnt vmcnt(0)
	s_barrier
	ds_read_b128 v[236:239], v254 offset:49152
	ds_read_b128 v[240:243], v254 offset:51200
	ds_read_b128 v[244:247], v254 offset:53248
	ds_read_b128 v[248:251], v254 offset:55296
	ds_read_b128 v[224:227], v252
	v_mfma_f32_16x16x32_bf16 v[64:67], v[228:231], v[162:165], v[64:67]
	v_mfma_f32_16x16x32_bf16 v[68:71], v[228:231], v[166:169], v[68:71]
	v_mfma_f32_16x16x32_bf16 v[72:75], v[228:231], v[170:173], v[72:75]
	v_mfma_f32_16x16x32_bf16 v[76:79], v[228:231], v[174:177], v[76:79]
	ds_read_b128 v[228:231], v252 offset:2048
	v_mfma_f32_16x16x32_bf16 v[80:83], v[232:235], v[162:165], v[80:83]
	v_mfma_f32_16x16x32_bf16 v[84:87], v[232:235], v[166:169], v[84:87]
	v_mfma_f32_16x16x32_bf16 v[88:91], v[232:235], v[170:173], v[88:91]
	v_mfma_f32_16x16x32_bf16 v[92:95], v[232:235], v[174:177], v[92:95]
	s_add_u32 s15, s15, 2
	s_branch .Lga16_loop
; template <int EPI, int MI>
; DI void gemm_tile(const GemmDesc& g, int tm, int tn, char* smem) {
;     ...
;   for (int kt = 0; kt < nk; kt += 2) {
;     if (kt + 1 < nk) G_GLDS(kt + 1, 1);
;     G_COMPUTE(0);
;     asm volatile("s_waitcnt vmcnt(0)" ::: "memory");
;     __syncthreads();
;     if (kt + 1 < nk) {
;       if (kt + 2 < nk) G_GLDS(kt + 2, 0);
;       G_COMPUTE(1);
;       asm volatile("s_waitcnt vmcnt(0)" ::: "memory");
;       __syncthreads();
;     }
;   }
.Lga16_last:
	ds_read_b128 v[232:235], v252 offset:28672
	s_waitcnt lgkmcnt(2)
	v_mfma_f32_16x16x32_bf16 v[0:3], v[224:227], v[236:239], v[0:3]
	v_mfma_f32_16x16x32_bf16 v[4:7], v[224:227], v[240:243], v[4:7]
	v_mfma_f32_16x16x32_bf16 v[8:11], v[224:227], v[244:247], v[8:11]
	v_mfma_f32_16x16x32_bf16 v[12:15], v[224:227], v[248:251], v[12:15]
	ds_read_b128 v[224:227], v252 offset:30720
	s_waitcnt lgkmcnt(2)
	v_mfma_f32_16x16x32_bf16 v[16:19], v[228:231], v[236:239], v[16:19]
	v_mfma_f32_16x16x32_bf16 v[20:23], v[228:231], v[240:243], v[20:23]
	v_mfma_f32_16x16x32_bf16 v[24:27], v[228:231], v[244:247], v[24:27]
	v_mfma_f32_16x16x32_bf16 v[28:31], v[228:231], v[248:251], v[28:31]
	ds_read_b128 v[228:231], v252 offset:32768
	s_waitcnt lgkmcnt(2)
	v_mfma_f32_16x16x32_bf16 v[32:35], v[232:235], v[236:239], v[32:35]
	v_mfma_f32_16x16x32_bf16 v[36:39], v[232:235], v[240:243], v[36:39]
	v_mfma_f32_16x16x32_bf16 v[40:43], v[232:235], v[244:247], v[40:43]
	v_mfma_f32_16x16x32_bf16 v[44:47], v[232:235], v[248:251], v[44:47]
	ds_read_b128 v[232:235], v252 offset:34816
	s_waitcnt lgkmcnt(2)
	v_mfma_f32_16x16x32_bf16 v[48:51], v[224:227], v[236:239], v[48:51]
	v_mfma_f32_16x16x32_bf16 v[52:55], v[224:227], v[240:243], v[52:55]
	v_mfma_f32_16x16x32_bf16 v[56:59], v[224:227], v[244:247], v[56:59]
	v_mfma_f32_16x16x32_bf16 v[60:63], v[224:227], v[248:251], v[60:63]
	ds_read_b128 v[162:165], v107
	ds_read_b128 v[166:169], v107 offset:2048
	ds_read_b128 v[170:173], v107 offset:4096
	ds_read_b128 v[174:177], v107 offset:6144
	ds_read_b128 v[224:227], v253 offset:24576
	s_waitcnt lgkmcnt(6)
	v_mfma_f32_16x16x32_bf16 v[64:67], v[228:231], v[236:239], v[64:67]
	v_mfma_f32_16x16x32_bf16 v[68:71], v[228:231], v[240:243], v[68:71]
	v_mfma_f32_16x16x32_bf16 v[72:75], v[228:231], v[244:247], v[72:75]
	v_mfma_f32_16x16x32_bf16 v[76:79], v[228:231], v[248:251], v[76:79]
	ds_read_b128 v[228:231], v253 offset:26624
	s_waitcnt lgkmcnt(6)
	v_mfma_f32_16x16x32_bf16 v[80:83], v[232:235], v[236:239], v[80:83]
	v_mfma_f32_16x16x32_bf16 v[84:87], v[232:235], v[240:243], v[84:87]
	v_mfma_f32_16x16x32_bf16 v[88:91], v[232:235], v[244:247], v[88:91]
	v_mfma_f32_16x16x32_bf16 v[92:95], v[232:235], v[248:251], v[92:95]
	ds_read_b128 v[232:235], v253 offset:28672
	s_waitcnt lgkmcnt(2)
	v_mfma_f32_16x16x32_bf16 v[0:3], v[224:227], v[162:165], v[0:3]
	v_mfma_f32_16x16x32_bf16 v[4:7], v[224:227], v[166:169], v[4:7]
	v_mfma_f32_16x16x32_bf16 v[8:11], v[224:227], v[170:173], v[8:11]
	v_mfma_f32_16x16x32_bf16 v[12:15], v[224:227], v[174:177], v[12:15]
	ds_read_b128 v[224:227], v253 offset:30720
	s_waitcnt lgkmcnt(2)
	v_mfma_f32_16x16x32_bf16 v[16:19], v[228:231], v[162:165], v[16:19]
	v_mfma_f32_16x16x32_bf16 v[20:23], v[228:231], v[166:169], v[20:23]
	v_mfma_f32_16x16x32_bf16 v[24:27], v[228:231], v[170:173], v[24:27]
	v_mfma_f32_16x16x32_bf16 v[28:31], v[228:231], v[174:177], v[28:31]
	ds_read_b128 v[228:231], v253 offset:32768
	s_waitcnt lgkmcnt(2)
	v_mfma_f32_16x16x32_bf16 v[32:35], v[232:235], v[162:165], v[32:35]
	v_mfma_f32_16x16x32_bf16 v[36:39], v[232:235], v[166:169], v[36:39]
	v_mfma_f32_16x16x32_bf16 v[40:43], v[232:235], v[170:173], v[40:43]
	v_mfma_f32_16x16x32_bf16 v[44:47], v[232:235], v[174:177], v[44:47]
	ds_read_b128 v[232:235], v253 offset:34816
	s_waitcnt lgkmcnt(2)
	v_mfma_f32_16x16x32_bf16 v[48:51], v[224:227], v[162:165], v[48:51]
	v_mfma_f32_16x16x32_bf16 v[52:55], v[224:227], v[166:169], v[52:55]
	v_mfma_f32_16x16x32_bf16 v[56:59], v[224:227], v[170:173], v[56:59]
	v_mfma_f32_16x16x32_bf16 v[60:63], v[224:227], v[174:177], v[60:63]
	s_waitcnt lgkmcnt(0)
	s_barrier
	v_mfma_f32_16x16x32_bf16 v[64:67], v[228:231], v[162:165], v[64:67]
	v_mfma_f32_16x16x32_bf16 v[68:71], v[228:231], v[166:169], v[68:71]
	v_mfma_f32_16x16x32_bf16 v[72:75], v[228:231], v[170:173], v[72:75]
	v_mfma_f32_16x16x32_bf16 v[76:79], v[228:231], v[174:177], v[76:79]
	v_mfma_f32_16x16x32_bf16 v[80:83], v[232:235], v[162:165], v[80:83]
	v_mfma_f32_16x16x32_bf16 v[84:87], v[232:235], v[166:169], v[84:87]
	v_mfma_f32_16x16x32_bf16 v[88:91], v[232:235], v[170:173], v[88:91]
	v_mfma_f32_16x16x32_bf16 v[92:95], v[232:235], v[174:177], v[92:95]
	s_branch .LBB0_201
